# G1 K-loop: third STAGE (2 LDS-DMA loads) of the 6-load phases moved from the load segment into the MFMA block; those phases wait vmcnt(6)
# baseline (speedup 1.0000x reference)
; #define PG8_STAGE(bufoff, gbase, voff) do { _Pragma("unroll") for (int _i = 0; _i < 2; ++_i) \
;         __builtin_amdgcn_global_load_lds((const unsigned*)((const char*)(gbase) + (voff)[_i]), (LAS unsigned*)(lds + (bufoff) + ldsw + _i * 8192), 16, 0, 0); } while (0)
; #define PG8_LDA(dst, b, h) do { _Pragma("unroll") for (int m = 0; m < 4; ++m) _Pragma("unroll") for (int k = 0; k < 2; ++k) dst[m][k] = *(const LAS bf16x8*)(lds + PG8_SA(b, h) + aoff + m * 2048 + k * 1024); } while (0)
; #define PG8_LDB(dst, b, h) do { _Pragma("unroll") for (int n = 0; n < 2; ++n) _Pragma("unroll") for (int k = 0; k < 2; ++k) dst[n][k] = *(const LAS bf16x8*)(lds + PG8_SB(b, h) + boff + n * 2048 + k * 1024); } while (0)
; #define PG8_MMA(ai, bj, At, Bt) do { __builtin_amdgcn_s_setprio(1); _Pragma("unroll") for (int m = 0; m < 4; ++m) _Pragma("unroll") for (int n = 0; n < 2; ++n) _Pragma("unroll") for (int k = 0; k < 2; ++k) \
;         acc[ai][bj][m][n] = __builtin_amdgcn_mfma_f32_16x16x32_bf16(Bt[n][k], At[m][k], acc[ai][bj][m][n], 0, 0, 0); __builtin_amdgcn_s_setprio(0); } while (0)
; #define PG8_WAIT_V(n) asm volatile("s_waitcnt vmcnt(" #n ")" ::: "memory")
; #define PG8_WAIT_L(n) asm volatile("s_waitcnt lgkmcnt(" #n ")" ::: "memory")
; template <bool HALFSKIP, bool SP2, bool ALIGN, class Epi>
; __device__ __forceinline__ void gemm_phase(LAS unsigned char* lds, const Gemm g, const StaticOrder& S, const Epi& E, const int wv) {
;     ...
;         for (int t = 0; t < nt; t += 2) {
;             const bool last = (t == nt - 2);
;             const char* a1 = cA + (size_t)(t + 1) * kstep;
;             const char* a2 = last ? nA : cA + (size_t)(t + 2) * kstep; const char* b2 = last ? nB : cB + (size_t)(t + 2) * kstep;
;             const char* a3 = a2 + kstep; const char* b3 = b2 + kstep;
;             if constexpr (SP2) {
;             PG8_LDB(B0, 0, 0); PG8_LDB(B1, 0, 1); PG8_SCHED; PG8_LDA(At, 0, 0); PG8_STAGE(PG8_SA(1, 1), a1 + hstep, voffA);
;             PG8_WAIT_V(8); PG8_WAIT_L(0); PG8_BAR; PG8_MMA(0, 0, At, B0); PG8_MMA(0, 1, At, B1); PG8_BAR; PG8_SCHED;
;             PG8_LDA(At, 0, 1); PG8_STAGE(PG8_SB(0, 0), b2, voffB); PG8_STAGE(PG8_SB(0, 1), b2 + hstep, voffB); PG8_STAGE(PG8_SA(0, 0), a2, voffA);
;             PG8_WAIT_V(8); PG8_WAIT_L(0); PG8_BAR; if (!halfu) { PG8_MMA(1, 0, At, B0); PG8_MMA(1, 1, At, B1); } PG8_BAR; PG8_SCHED;
.LBB0_71:
	s_add_u32 s8, s4, 0xfff80080
	s_addc_u32 s9, s5, -1
	s_add_i32 s49, 16, 0x10000
	s_cmp_eq_u32 s47, 28
	s_cselect_b32 s15, s1, s9
	s_cselect_b32 s14, s3, s8
	v_add_u32_e32 v8, s49, v177
	s_cselect_b32 s9, s38, s41
	s_cselect_b32 s8, s39, s40
	s_add_i32 s57, 16, 0x14000
	ds_read_b128 v[130:133], v8
	ds_read_b128 v[134:137], v8 offset:1024
	ds_read_b128 v[150:153], v8 offset:2048
	ds_read_b128 v[154:157], v8 offset:3072
	v_add_u32_e32 v8, s57, v177
	ds_read_b128 v[158:161], v8
	ds_read_b128 v[162:165], v8 offset:1024
	ds_read_b128 v[166:169], v8 offset:2048
	ds_read_b128 v[170:173], v8 offset:3072
	v_lshl_add_u64 v[174:175], s[4:5], 0, v[146:147]
	s_add_i32 m0, s20, 0xc000
	ds_read_b128 v[180:183], v179
	ds_read_b128 v[184:187], v179 offset:1024
	ds_read_b128 v[188:191], v179 offset:2048
	ds_read_b128 v[204:207], v179 offset:3072
	ds_read_b128 v[208:211], v179 offset:4096
	ds_read_b128 v[212:215], v179 offset:5120
	ds_read_b128 v[216:219], v179 offset:6144
	ds_read_b128 v[220:223], v179 offset:7168
	global_load_lds_dwordx4 v[174:175], off
	v_lshl_add_u64 v[174:175], s[4:5], 0, v[148:149]
	s_add_i32 m0, s20, 0xe000
	s_nop 0
	global_load_lds_dwordx4 v[174:175], off
	s_waitcnt vmcnt(8)
	s_waitcnt lgkmcnt(0)
	s_barrier
	s_setprio 1
	s_waitcnt lgkmcnt(0)
	v_mfma_f32_16x16x32_bf16 v[126:129], v[130:133], v[180:183], v[126:129]
	v_mfma_f32_16x16x32_bf16 v[122:125], v[150:153], v[180:183], v[122:125]
	v_mfma_f32_16x16x32_bf16 v[110:113], v[130:133], v[188:191], v[110:113]
	v_mfma_f32_16x16x32_bf16 v[106:109], v[150:153], v[188:191], v[106:109]
	v_mfma_f32_16x16x32_bf16 v[94:97], v[130:133], v[208:211], v[94:97]
	v_mfma_f32_16x16x32_bf16 v[90:93], v[150:153], v[208:211], v[90:93]
	v_mfma_f32_16x16x32_bf16 v[78:81], v[130:133], v[216:219], v[78:81]
	v_mfma_f32_16x16x32_bf16 v[74:77], v[150:153], v[216:219], v[74:77]
	v_mfma_f32_16x16x32_bf16 v[126:129], v[134:137], v[184:187], v[126:129]
	v_mfma_f32_16x16x32_bf16 v[122:125], v[154:157], v[184:187], v[122:125]
	v_mfma_f32_16x16x32_bf16 v[110:113], v[134:137], v[204:207], v[110:113]
	v_mfma_f32_16x16x32_bf16 v[106:109], v[154:157], v[204:207], v[106:109]
	v_mfma_f32_16x16x32_bf16 v[94:97], v[134:137], v[212:215], v[94:97]
	v_mfma_f32_16x16x32_bf16 v[90:93], v[154:157], v[212:215], v[90:93]
	v_mfma_f32_16x16x32_bf16 v[78:81], v[134:137], v[220:223], v[78:81]
	v_mfma_f32_16x16x32_bf16 v[74:77], v[154:157], v[220:223], v[74:77]
	s_setprio 0
	s_setprio 1
	v_mfma_f32_16x16x32_bf16 v[118:121], v[158:161], v[180:183], v[118:121]
	v_mfma_f32_16x16x32_bf16 v[114:117], v[166:169], v[180:183], v[114:117]
	v_mfma_f32_16x16x32_bf16 v[102:105], v[158:161], v[188:191], v[102:105]
	v_mfma_f32_16x16x32_bf16 v[98:101], v[166:169], v[188:191], v[98:101]
	v_mfma_f32_16x16x32_bf16 v[86:89], v[158:161], v[208:211], v[86:89]
	v_mfma_f32_16x16x32_bf16 v[82:85], v[166:169], v[208:211], v[82:85]
	v_mfma_f32_16x16x32_bf16 v[70:73], v[158:161], v[216:219], v[70:73]
	v_mfma_f32_16x16x32_bf16 v[66:69], v[166:169], v[216:219], v[66:69]
	v_mfma_f32_16x16x32_bf16 v[118:121], v[162:165], v[184:187], v[118:121]
	v_mfma_f32_16x16x32_bf16 v[114:117], v[170:173], v[184:187], v[114:117]
	v_mfma_f32_16x16x32_bf16 v[102:105], v[162:165], v[204:207], v[102:105]
	v_mfma_f32_16x16x32_bf16 v[98:101], v[170:173], v[204:207], v[98:101]
	v_mfma_f32_16x16x32_bf16 v[86:89], v[162:165], v[212:215], v[86:89]
	v_mfma_f32_16x16x32_bf16 v[82:85], v[170:173], v[212:215], v[82:85]
	v_mfma_f32_16x16x32_bf16 v[70:73], v[162:165], v[220:223], v[70:73]
	v_mfma_f32_16x16x32_bf16 v[66:69], v[170:173], v[220:223], v[66:69]
	s_setprio 0
	s_barrier
	s_add_i32 s49, s49, s19
	v_lshl_add_u64 v[174:175], s[8:9], 0, v[140:141]
	s_mov_b32 m0, s49
	ds_read_b128 v[180:183], v179 offset:16384
	ds_read_b128 v[184:187], v179 offset:17408
	ds_read_b128 v[188:191], v179 offset:18432
	ds_read_b128 v[204:207], v179 offset:19456
	ds_read_b128 v[208:211], v179 offset:20480
	ds_read_b128 v[212:215], v179 offset:21504
	ds_read_b128 v[216:219], v179 offset:22528
	ds_read_b128 v[220:223], v179 offset:23552
	global_load_lds_dwordx4 v[174:175], off
	s_add_i32 m0, s49, 0x2000
	s_add_u32 s58, s8, 0x80000
	v_lshl_add_u64 v[192:193], s[8:9], 0, v[144:145]
	s_addc_u32 s59, s9, 0
	s_add_i32 s49, s57, s19
	global_load_lds_dwordx4 v[192:193], off
	v_lshl_add_u64 v[224:225], s[58:59], 0, v[140:141]
	s_mov_b32 m0, s49
	v_lshl_add_u64 v[226:227], s[14:15], 0, v[142:143]
	global_load_lds_dwordx4 v[224:225], off
	v_lshl_add_u64 v[224:225], s[58:59], 0, v[144:145]
	s_add_i32 m0, s49, 0x2000
	s_nop 0
	global_load_lds_dwordx4 v[224:225], off
	s_waitcnt vmcnt(6)
	s_waitcnt lgkmcnt(0)
	s_barrier
; #define PG8_STAGE(bufoff, gbase, voff) do { _Pragma("unroll") for (int _i = 0; _i < 2; ++_i) \
;         __builtin_amdgcn_global_load_lds((const unsigned*)((const char*)(gbase) + (voff)[_i]), (LAS unsigned*)(lds + (bufoff) + ldsw + _i * 8192), 16, 0, 0); } while (0)
; #define PG8_LDA(dst, b, h) do { _Pragma("unroll") for (int m = 0; m < 4; ++m) _Pragma("unroll") for (int k = 0; k < 2; ++k) dst[m][k] = *(const LAS bf16x8*)(lds + PG8_SA(b, h) + aoff + m * 2048 + k * 1024); } while (0)
; #define PG8_LDB(dst, b, h) do { _Pragma("unroll") for (int n = 0; n < 2; ++n) _Pragma("unroll") for (int k = 0; k < 2; ++k) dst[n][k] = *(const LAS bf16x8*)(lds + PG8_SB(b, h) + boff + n * 2048 + k * 1024); } while (0)
; #define PG8_MMA(ai, bj, At, Bt) do { __builtin_amdgcn_s_setprio(1); _Pragma("unroll") for (int m = 0; m < 4; ++m) _Pragma("unroll") for (int n = 0; n < 2; ++n) _Pragma("unroll") for (int k = 0; k < 2; ++k) \
;         acc[ai][bj][m][n] = __builtin_amdgcn_mfma_f32_16x16x32_bf16(Bt[n][k], At[m][k], acc[ai][bj][m][n], 0, 0, 0); __builtin_amdgcn_s_setprio(0); } while (0)
; #define PG8_WAIT_V(n) asm volatile("s_waitcnt vmcnt(" #n ")" ::: "memory")
; #define PG8_WAIT_L(n) asm volatile("s_waitcnt lgkmcnt(" #n ")" ::: "memory")
; #define PG8_BAR __builtin_amdgcn_s_barrier()
; #define PG8_SCHED __builtin_amdgcn_sched_barrier(0)
; template <bool HALFSKIP, bool SP2, bool ALIGN, class Epi>
; __device__ __forceinline__ void gemm_phase(LAS unsigned char* lds, const Gemm g, const StaticOrder& S, const Epi& E, const int wv) {
;     ...
;             PG8_WAIT_V(8); PG8_WAIT_L(0); PG8_BAR; PG8_MMA(0, 0, At, B0); PG8_MMA(0, 1, At, B1); PG8_BAR; PG8_SCHED;
;             PG8_LDA(At, 0, 1); PG8_STAGE(PG8_SB(0, 0), b2, voffB); PG8_STAGE(PG8_SB(0, 1), b2 + hstep, voffB); PG8_STAGE(PG8_SA(0, 0), a2, voffA);
;             PG8_WAIT_V(8); PG8_WAIT_L(0); PG8_BAR; if (!halfu) { PG8_MMA(1, 0, At, B0); PG8_MMA(1, 1, At, B1); } PG8_BAR; PG8_SCHED;
;             PG8_LDB(B0, 1, 0); PG8_LDB(B1, 1, 1); PG8_SCHED; PG8_LDA(At, 1, 0); PG8_STAGE(PG8_SA(0, 1), a2 + hstep, voffA);
;             PG8_WAIT_V(8); PG8_WAIT_L(0); PG8_BAR; PG8_MMA(0, 0, At, B0); PG8_MMA(0, 1, At, B1); PG8_BAR; PG8_SCHED;
	s_setprio 1
	s_waitcnt lgkmcnt(0)
	v_mfma_f32_16x16x32_bf16 v[62:65], v[130:133], v[180:183], v[62:65]
	v_mfma_f32_16x16x32_bf16 v[58:61], v[150:153], v[180:183], v[58:61]
	v_mfma_f32_16x16x32_bf16 v[46:49], v[130:133], v[188:191], v[46:49]
	v_mfma_f32_16x16x32_bf16 v[42:45], v[150:153], v[188:191], v[42:45]
	v_lshl_add_u64 v[224:225], s[14:15], 0, v[138:139]
	s_mov_b32 m0, s20
	s_nop 0
	global_load_lds_dwordx4 v[224:225], off
	v_mfma_f32_16x16x32_bf16 v[30:33], v[130:133], v[208:211], v[30:33]
	v_mfma_f32_16x16x32_bf16 v[26:29], v[150:153], v[208:211], v[26:29]
	v_mfma_f32_16x16x32_bf16 v[14:17], v[130:133], v[216:219], v[14:17]
	v_mfma_f32_16x16x32_bf16 v[10:13], v[150:153], v[216:219], v[10:13]
	v_mfma_f32_16x16x32_bf16 v[62:65], v[134:137], v[184:187], v[62:65]
	v_mfma_f32_16x16x32_bf16 v[58:61], v[154:157], v[184:187], v[58:61]
	s_mov_b32 m0, s21
	s_nop 0
	global_load_lds_dwordx4 v[226:227], off
	v_mfma_f32_16x16x32_bf16 v[46:49], v[134:137], v[204:207], v[46:49]
	v_mfma_f32_16x16x32_bf16 v[42:45], v[154:157], v[204:207], v[42:45]
	v_mfma_f32_16x16x32_bf16 v[30:33], v[134:137], v[212:215], v[30:33]
	v_mfma_f32_16x16x32_bf16 v[26:29], v[154:157], v[212:215], v[26:29]
	v_mfma_f32_16x16x32_bf16 v[14:17], v[134:137], v[220:223], v[14:17]
	v_mfma_f32_16x16x32_bf16 v[10:13], v[154:157], v[220:223], v[10:13]
	s_setprio 0
	s_setprio 1
	v_mfma_f32_16x16x32_bf16 v[54:57], v[158:161], v[180:183], v[54:57]
	v_mfma_f32_16x16x32_bf16 v[50:53], v[166:169], v[180:183], v[50:53]
	v_mfma_f32_16x16x32_bf16 v[38:41], v[158:161], v[188:191], v[38:41]
	v_mfma_f32_16x16x32_bf16 v[34:37], v[166:169], v[188:191], v[34:37]
	v_mfma_f32_16x16x32_bf16 v[22:25], v[158:161], v[208:211], v[22:25]
	v_mfma_f32_16x16x32_bf16 v[18:21], v[166:169], v[208:211], v[18:21]
	v_mfma_f32_16x16x32_bf16 v[4:7], v[158:161], v[216:219], v[4:7]
	v_mfma_f32_16x16x32_bf16 v[0:3], v[166:169], v[216:219], v[0:3]
	v_mfma_f32_16x16x32_bf16 v[54:57], v[162:165], v[184:187], v[54:57]
	v_mfma_f32_16x16x32_bf16 v[50:53], v[170:173], v[184:187], v[50:53]
	v_mfma_f32_16x16x32_bf16 v[38:41], v[162:165], v[204:207], v[38:41]
	v_mfma_f32_16x16x32_bf16 v[34:37], v[170:173], v[204:207], v[34:37]
	v_mfma_f32_16x16x32_bf16 v[22:25], v[162:165], v[212:215], v[22:25]
	v_mfma_f32_16x16x32_bf16 v[18:21], v[170:173], v[212:215], v[18:21]
	v_mfma_f32_16x16x32_bf16 v[4:7], v[162:165], v[220:223], v[4:7]
	v_mfma_f32_16x16x32_bf16 v[0:3], v[170:173], v[220:223], v[0:3]
	s_setprio 0
	s_barrier
	s_add_i32 s49, 16, 0x18000
	v_add_u32_e32 v8, s49, v177
	s_add_i32 s57, 16, 0x1c000
	ds_read_b128 v[130:133], v8
	ds_read_b128 v[134:137], v8 offset:1024
	ds_read_b128 v[150:153], v8 offset:2048
	ds_read_b128 v[154:157], v8 offset:3072
	v_add_u32_e32 v8, s57, v177
	ds_read_b128 v[158:161], v8
	ds_read_b128 v[162:165], v8 offset:1024
	ds_read_b128 v[166:169], v8 offset:2048
	ds_read_b128 v[170:173], v8 offset:3072
	s_add_u32 s14, s14, 0x80000
	s_addc_u32 s15, s15, 0
	s_mov_b32 m0, s22
	v_lshl_add_u64 v[228:229], s[14:15], 0, v[138:139]
	ds_read_b128 v[180:183], v179 offset:32768
	ds_read_b128 v[184:187], v179 offset:33792
	ds_read_b128 v[188:191], v179 offset:34816
	ds_read_b128 v[204:207], v179 offset:35840
	ds_read_b128 v[208:211], v179 offset:36864
	ds_read_b128 v[212:215], v179 offset:37888
	ds_read_b128 v[216:219], v179 offset:38912
	ds_read_b128 v[220:223], v179 offset:39936
	global_load_lds_dwordx4 v[228:229], off
	v_lshl_add_u64 v[228:229], s[14:15], 0, v[142:143]
	s_mov_b32 m0, s23
	s_nop 0
	global_load_lds_dwordx4 v[228:229], off
	s_waitcnt vmcnt(8)
	s_waitcnt lgkmcnt(0)
	s_barrier
	s_setprio 1
	s_waitcnt lgkmcnt(0)
	v_mfma_f32_16x16x32_bf16 v[126:129], v[130:133], v[180:183], v[126:129]
	v_mfma_f32_16x16x32_bf16 v[122:125], v[150:153], v[180:183], v[122:125]
	v_mfma_f32_16x16x32_bf16 v[110:113], v[130:133], v[188:191], v[110:113]
	v_mfma_f32_16x16x32_bf16 v[106:109], v[150:153], v[188:191], v[106:109]
	v_mfma_f32_16x16x32_bf16 v[94:97], v[130:133], v[208:211], v[94:97]
	v_mfma_f32_16x16x32_bf16 v[90:93], v[150:153], v[208:211], v[90:93]
	v_mfma_f32_16x16x32_bf16 v[78:81], v[130:133], v[216:219], v[78:81]
	v_mfma_f32_16x16x32_bf16 v[74:77], v[150:153], v[216:219], v[74:77]
	v_mfma_f32_16x16x32_bf16 v[126:129], v[134:137], v[184:187], v[126:129]
	v_mfma_f32_16x16x32_bf16 v[122:125], v[154:157], v[184:187], v[122:125]
	v_mfma_f32_16x16x32_bf16 v[110:113], v[134:137], v[204:207], v[110:113]
	v_mfma_f32_16x16x32_bf16 v[106:109], v[154:157], v[204:207], v[106:109]
	v_mfma_f32_16x16x32_bf16 v[94:97], v[134:137], v[212:215], v[94:97]
	v_mfma_f32_16x16x32_bf16 v[90:93], v[154:157], v[212:215], v[90:93]
	v_mfma_f32_16x16x32_bf16 v[78:81], v[134:137], v[220:223], v[78:81]
	v_mfma_f32_16x16x32_bf16 v[74:77], v[154:157], v[220:223], v[74:77]
	s_setprio 0
	s_setprio 1
	v_mfma_f32_16x16x32_bf16 v[118:121], v[158:161], v[180:183], v[118:121]
	v_mfma_f32_16x16x32_bf16 v[114:117], v[166:169], v[180:183], v[114:117]
	v_mfma_f32_16x16x32_bf16 v[102:105], v[158:161], v[188:191], v[102:105]
	v_mfma_f32_16x16x32_bf16 v[98:101], v[166:169], v[188:191], v[98:101]
	v_mfma_f32_16x16x32_bf16 v[86:89], v[158:161], v[208:211], v[86:89]
	v_mfma_f32_16x16x32_bf16 v[82:85], v[166:169], v[208:211], v[82:85]
	v_mfma_f32_16x16x32_bf16 v[70:73], v[158:161], v[216:219], v[70:73]
	v_mfma_f32_16x16x32_bf16 v[66:69], v[166:169], v[216:219], v[66:69]
	v_mfma_f32_16x16x32_bf16 v[118:121], v[162:165], v[184:187], v[118:121]
	v_mfma_f32_16x16x32_bf16 v[114:117], v[170:173], v[184:187], v[114:117]
	v_mfma_f32_16x16x32_bf16 v[102:105], v[162:165], v[204:207], v[102:105]
	v_mfma_f32_16x16x32_bf16 v[98:101], v[170:173], v[204:207], v[98:101]
	v_mfma_f32_16x16x32_bf16 v[86:89], v[162:165], v[212:215], v[86:89]
	v_mfma_f32_16x16x32_bf16 v[82:85], v[170:173], v[212:215], v[82:85]
	v_mfma_f32_16x16x32_bf16 v[70:73], v[162:165], v[220:223], v[70:73]
	v_mfma_f32_16x16x32_bf16 v[66:69], v[170:173], v[220:223], v[66:69]
	s_setprio 0
	s_barrier
; #define PG8_STAGE(bufoff, gbase, voff) do { _Pragma("unroll") for (int _i = 0; _i < 2; ++_i) \
;         __builtin_amdgcn_global_load_lds((const unsigned*)((const char*)(gbase) + (voff)[_i]), (LAS unsigned*)(lds + (bufoff) + ldsw + _i * 8192), 16, 0, 0); } while (0)
; #define PG8_LDA(dst, b, h) do { _Pragma("unroll") for (int m = 0; m < 4; ++m) _Pragma("unroll") for (int k = 0; k < 2; ++k) dst[m][k] = *(const LAS bf16x8*)(lds + PG8_SA(b, h) + aoff + m * 2048 + k * 1024); } while (0)
; #define PG8_LDB(dst, b, h) do { _Pragma("unroll") for (int n = 0; n < 2; ++n) _Pragma("unroll") for (int k = 0; k < 2; ++k) dst[n][k] = *(const LAS bf16x8*)(lds + PG8_SB(b, h) + boff + n * 2048 + k * 1024); } while (0)
; #define PG8_MMA(ai, bj, At, Bt) do { __builtin_amdgcn_s_setprio(1); _Pragma("unroll") for (int m = 0; m < 4; ++m) _Pragma("unroll") for (int n = 0; n < 2; ++n) _Pragma("unroll") for (int k = 0; k < 2; ++k) \
;         acc[ai][bj][m][n] = __builtin_amdgcn_mfma_f32_16x16x32_bf16(Bt[n][k], At[m][k], acc[ai][bj][m][n], 0, 0, 0); __builtin_amdgcn_s_setprio(0); } while (0)
; #define PG8_WAIT_V(n) asm volatile("s_waitcnt vmcnt(" #n ")" ::: "memory")
; #define PG8_WAIT_L(n) asm volatile("s_waitcnt lgkmcnt(" #n ")" ::: "memory")
; #define PG8_BAR __builtin_amdgcn_s_barrier()
; #define PG8_SCHED __builtin_amdgcn_sched_barrier(0)
; template <bool HALFSKIP, bool SP2, bool ALIGN, class Epi>
; __device__ __forceinline__ void gemm_phase(LAS unsigned char* lds, const Gemm g, const StaticOrder& S, const Epi& E, const int wv) {
;     ...
;         for (int t = 0; t < nt; t += 2) {
;     ...
;             PG8_LDB(B0, 1, 0); PG8_LDB(B1, 1, 1); PG8_SCHED; PG8_LDA(At, 1, 0); PG8_STAGE(PG8_SA(0, 1), a2 + hstep, voffA);
;             PG8_WAIT_V(8); PG8_WAIT_L(0); PG8_BAR; PG8_MMA(0, 0, At, B0); PG8_MMA(0, 1, At, B1); PG8_BAR; PG8_SCHED;
;             PG8_LDA(At, 1, 1); PG8_STAGE(PG8_SB(1, 0), b3, voffB); PG8_STAGE(PG8_SB(1, 1), b3 + hstep, voffB); PG8_STAGE(PG8_SA(1, 0), a3, voffA);
;             PG8_WAIT_V(8); PG8_WAIT_L(0); PG8_BAR; if (!halfu) { PG8_MMA(1, 0, At, B0); PG8_MMA(1, 1, At, B1); } PG8_BAR; PG8_SCHED;
	s_add_i32 s14, s49, s19
	v_lshl_add_u64 v[174:175], v[174:175], 0, s[16:17]
	s_mov_b32 m0, s14
	ds_read_b128 v[180:183], v179 offset:49152
	ds_read_b128 v[184:187], v179 offset:50176
	ds_read_b128 v[188:191], v179 offset:51200
	ds_read_b128 v[204:207], v179 offset:52224
	ds_read_b128 v[208:211], v179 offset:53248
	ds_read_b128 v[212:215], v179 offset:54272
	ds_read_b128 v[216:219], v179 offset:55296
	ds_read_b128 v[220:223], v179 offset:56320
	global_load_lds_dwordx4 v[174:175], off
	s_add_i32 m0, s14, 0x2000
	s_add_u32 s8, s8, 0x80080
	v_lshl_add_u64 v[174:175], v[192:193], 0, s[16:17]
	s_addc_u32 s9, s9, 0
	s_add_i32 s14, s57, s19
	global_load_lds_dwordx4 v[174:175], off
	v_lshl_add_u64 v[174:175], s[8:9], 0, v[140:141]
	s_mov_b32 m0, s14
	s_nop 0
	global_load_lds_dwordx4 v[174:175], off
	v_lshl_add_u64 v[174:175], s[8:9], 0, v[144:145]
	s_add_i32 m0, s14, 0x2000
	s_nop 0
	global_load_lds_dwordx4 v[174:175], off
	s_waitcnt vmcnt(6)
	s_waitcnt lgkmcnt(0)
	s_barrier
	s_setprio 1
	s_waitcnt lgkmcnt(0)
	v_mfma_f32_16x16x32_bf16 v[62:65], v[130:133], v[180:183], v[62:65]
	v_mfma_f32_16x16x32_bf16 v[58:61], v[150:153], v[180:183], v[58:61]
	v_mfma_f32_16x16x32_bf16 v[46:49], v[130:133], v[188:191], v[46:49]
	v_mfma_f32_16x16x32_bf16 v[42:45], v[150:153], v[188:191], v[42:45]
	v_lshl_add_u64 v[174:175], v[224:225], 0, s[16:17]
	s_mov_b32 m0, s25
	s_nop 0
	global_load_lds_dwordx4 v[174:175], off
	v_mfma_f32_16x16x32_bf16 v[30:33], v[130:133], v[208:211], v[30:33]
	v_mfma_f32_16x16x32_bf16 v[26:29], v[150:153], v[208:211], v[26:29]
	v_mfma_f32_16x16x32_bf16 v[14:17], v[130:133], v[216:219], v[14:17]
	v_mfma_f32_16x16x32_bf16 v[10:13], v[150:153], v[216:219], v[10:13]
	v_mfma_f32_16x16x32_bf16 v[62:65], v[134:137], v[184:187], v[62:65]
	v_mfma_f32_16x16x32_bf16 v[58:61], v[154:157], v[184:187], v[58:61]
	v_lshl_add_u64 v[174:175], v[226:227], 0, s[16:17]
	s_mov_b32 m0, s26
	s_nop 0
	global_load_lds_dwordx4 v[174:175], off
	v_mfma_f32_16x16x32_bf16 v[46:49], v[134:137], v[204:207], v[46:49]
	v_mfma_f32_16x16x32_bf16 v[42:45], v[154:157], v[204:207], v[42:45]
	v_mfma_f32_16x16x32_bf16 v[30:33], v[134:137], v[212:215], v[30:33]
	v_mfma_f32_16x16x32_bf16 v[26:29], v[154:157], v[212:215], v[26:29]
	v_mfma_f32_16x16x32_bf16 v[14:17], v[134:137], v[220:223], v[14:17]
	v_mfma_f32_16x16x32_bf16 v[10:13], v[154:157], v[220:223], v[10:13]
	s_setprio 0
	s_setprio 1
	v_mfma_f32_16x16x32_bf16 v[54:57], v[158:161], v[180:183], v[54:57]
	v_mfma_f32_16x16x32_bf16 v[50:53], v[166:169], v[180:183], v[50:53]
	v_mfma_f32_16x16x32_bf16 v[38:41], v[158:161], v[188:191], v[38:41]
	v_mfma_f32_16x16x32_bf16 v[34:37], v[166:169], v[188:191], v[34:37]
	v_mfma_f32_16x16x32_bf16 v[22:25], v[158:161], v[208:211], v[22:25]
	v_mfma_f32_16x16x32_bf16 v[18:21], v[166:169], v[208:211], v[18:21]
	v_mfma_f32_16x16x32_bf16 v[4:7], v[158:161], v[216:219], v[4:7]
	v_mfma_f32_16x16x32_bf16 v[0:3], v[166:169], v[216:219], v[0:3]
	v_mfma_f32_16x16x32_bf16 v[54:57], v[162:165], v[184:187], v[54:57]
	v_mfma_f32_16x16x32_bf16 v[50:53], v[170:173], v[184:187], v[50:53]
	v_mfma_f32_16x16x32_bf16 v[38:41], v[162:165], v[204:207], v[38:41]
	v_mfma_f32_16x16x32_bf16 v[34:37], v[170:173], v[204:207], v[34:37]
	v_mfma_f32_16x16x32_bf16 v[22:25], v[162:165], v[212:215], v[22:25]
	v_mfma_f32_16x16x32_bf16 v[18:21], v[170:173], v[212:215], v[18:21]
	v_mfma_f32_16x16x32_bf16 v[4:7], v[162:165], v[220:223], v[4:7]
	v_mfma_f32_16x16x32_bf16 v[0:3], v[170:173], v[220:223], v[0:3]
	s_setprio 0
	s_barrier
	s_add_i32 s47, s47, 2
	s_add_u32 s4, s4, 0x100
	s_addc_u32 s5, s5, 0
	s_add_u32 s40, s40, 0x100
	s_addc_u32 s41, s41, 0
	s_cmp_gt_u32 s47, 29
	s_cbranch_scc0 .LBB0_71
	s_and_b64 vcc, exec, s[44:45]
	s_cbranch_vccz .LBB0_74
	s_barrier
